# c41 + the L2 write-back (buffer_wbl2) dropped at the 8 grid barriers that follow phases whose every global store is now write-through
# speedup vs baseline: 1.0029x; 1.0029x over previous
.LBB0_835:
	s_andn2_saveexec_b64 s[0:1], s[12:13]
	s_cbranch_execz .LBB0_855
	s_mov_b64 s[12:13], exec
	s_nop 0
	s_waitcnt lgkmcnt(0)
	s_waitcnt vmcnt(0)
	v_mbcnt_lo_u32_b32 v1, s12, 0
	v_mbcnt_hi_u32_b32 v1, s13, v1
	v_cmp_eq_u32_e32 vcc, 0, v1
	s_and_saveexec_b64 s[14:15], vcc
	s_cbranch_execz .LBB0_838
	s_bcnt1_i32_b64 s0, s[12:13]
	v_mov_b32_e32 v2, 0x7000
	v_mov_b32_e32 v3, s0
	global_atomic_add v2, v2, v3, s[86:87] offset:1024 sc0

.LBB0_1892:
	s_andn2_saveexec_b64 s[6:7], s[6:7]
	s_cbranch_execz .LBB0_1912
	s_mov_b64 s[6:7], exec
	s_nop 0
	s_waitcnt lgkmcnt(0)
	s_waitcnt vmcnt(0)
	v_mbcnt_lo_u32_b32 v1, s6, 0
	v_mbcnt_hi_u32_b32 v1, s7, v1
	v_cmp_eq_u32_e32 vcc, 0, v1
	s_and_saveexec_b64 s[8:9], vcc
	s_cbranch_execz .LBB0_1895
	s_bcnt1_i32_b64 s6, s[6:7]
	v_mov_b32_e32 v2, 0x7000
	v_mov_b32_e32 v3, s6
	global_atomic_add v2, v2, v3, s[86:87] offset:1024 sc0
